# hot loop heads (five GEMM K loops, SSD chunk loop) aligned to 64 bytes
# baseline (speedup 1.0000x reference)
;     __device__ __forceinline__ const char* Ap(int part) const { return (const char*)A0 + (long)(part == 1) * ((const char*)A1 - (const char*)A0) + (long)(part == 2) * ((const char*)A2 - (const char*)A0); }
;     __device__ __forceinline__ const char* Bp(int part) const { return (const char*)B0 + (long)(part == 1) * ((const char*)B1 - (const char*)B0) + (long)(part == 2) * ((const char*)B2 - (const char*)B0); }
; template <class Epi, bool GS = false>
; __device__ __forceinline__ void gemm_phase(LAS unsigned char* lds, const Gemm g, const StaticOrder& S, const Epi& E, const int tid) {
;     ...
;         const bool has_next = S.next(ui + 1, nxt);
;         const char* nA = has_next ? g.Ap(nxt.part) + (size_t)nxt.pm * tstepA : cA; const char* nB = has_next ? g.Bp(nxt.part) + (size_t)nxt.pn * tstepB : cB;
;         const int nt = g.Kp(cur.part) / BK;
;         const int seg = (GS && cur.part == 0) ? 8 : nt;
;         for (int tg = 0; tg < nt; tg += seg) {
;         for (int t = tg; t < tg + seg; t += 2) {
;             const bool last = (t == nt - 2);
;             const char* a1 = cA + (size_t)(t + 1) * kstep;
;             const char* a2 = last ? nA : cA + (size_t)(t + 2) * kstep; const char* b2 = last ? nB : cB + (size_t)(t + 2) * kstep;
;             const char* a3 = a2 + kstep; const char* b3 = b2 + kstep;
;     ...
; #pragma unroll
;         for (int a = 0; a < 2; ++a)
; #pragma unroll
;             for (int b = 0; b < 2; ++b)
; #pragma unroll
;                 for (int m = 0; m < 4; ++m)
; #pragma unroll
;                     for (int n = 0; n < 2; ++n) acc[a][b][m][n] = (f32x4){0.f, 0.f, 0.f, 0.f};
.LBB0_204:
	s_ashr_i32 s21, s20, 31
	s_lshl_b64 s[22:23], s[20:21], 19
	s_add_u32 s22, s12, s22
	s_addc_u32 s23, s13, s23
	s_and_b64 s[42:43], s[4:5], exec
	s_cselect_b32 s21, s23, s45
	s_cselect_b32 s55, s22, s44
	s_ashr_i32 s17, s16, 31
	s_lshl_b64 s[42:43], s[16:17], 19
	v_readlane_b32 s17, v255, 20
	s_add_u32 s42, s17, s42
	v_readlane_b32 s17, v255, 22
	s_addc_u32 s43, s17, s43
	s_and_b64 s[48:49], s[4:5], exec
	s_cselect_b32 s17, s43, s47
	s_cselect_b32 s56, s42, s46
	s_add_u32 s44, s44, 0x40080
	s_addc_u32 s45, s45, 0
	s_add_u32 s57, s46, 0x100
	v_mov_b32_e32 v2, 0
	s_addc_u32 s58, s47, 0
	s_mov_b32 s59, -2
	v_mov_b32_e32 v3, v2
	v_mov_b32_e32 v4, v2
	v_mov_b32_e32 v5, v2
	v_mov_b32_e32 v6, v2
	v_mov_b32_e32 v7, v2
	v_mov_b32_e32 v8, v2
	v_mov_b32_e32 v9, v2
	v_mov_b32_e32 v10, v2
	v_mov_b32_e32 v11, v2
	v_mov_b32_e32 v12, v2
	v_mov_b32_e32 v13, v2
	v_mov_b32_e32 v18, v2
	v_mov_b32_e32 v19, v2
	v_mov_b32_e32 v20, v2
	v_mov_b32_e32 v21, v2
	v_mov_b32_e32 v26, v2
	v_mov_b32_e32 v27, v2
	v_mov_b32_e32 v28, v2
	v_mov_b32_e32 v29, v2
	v_mov_b32_e32 v34, v2
	v_mov_b32_e32 v35, v2
	v_mov_b32_e32 v36, v2
	v_mov_b32_e32 v37, v2
	v_mov_b32_e32 v42, v2
	v_mov_b32_e32 v43, v2
	v_mov_b32_e32 v44, v2
	v_mov_b32_e32 v45, v2
	s_waitcnt vmcnt(0)
	v_mov_b32_e32 v50, v2
	v_mov_b32_e32 v51, v2
	v_mov_b32_e32 v52, v2
	v_mov_b32_e32 v53, v2
	v_mov_b32_e32 v14, v2
	v_mov_b32_e32 v15, v2
	v_mov_b32_e32 v16, v2
	v_mov_b32_e32 v17, v2
	v_mov_b32_e32 v22, v2
	v_mov_b32_e32 v23, v2
	v_mov_b32_e32 v24, v2
	v_mov_b32_e32 v25, v2
	v_mov_b32_e32 v30, v2
	v_mov_b32_e32 v31, v2
	v_mov_b32_e32 v32, v2
	v_mov_b32_e32 v33, v2
	v_mov_b32_e32 v38, v2
	v_mov_b32_e32 v39, v2
	v_mov_b32_e32 v40, v2
	v_mov_b32_e32 v41, v2
	v_mov_b32_e32 v46, v2
	v_mov_b32_e32 v47, v2
	v_mov_b32_e32 v48, v2
	v_mov_b32_e32 v49, v2
	v_mov_b32_e32 v54, v2
	v_mov_b32_e32 v55, v2
	v_mov_b32_e32 v56, v2
	v_mov_b32_e32 v57, v2
	v_mov_b32_e32 v58, v2
	v_mov_b32_e32 v59, v2
	v_mov_b32_e32 v60, v2
	v_mov_b32_e32 v61, v2
	v_mov_b32_e32 v62, v2
	v_mov_b32_e32 v63, v2
	v_mov_b32_e32 v64, v2
	v_mov_b32_e32 v65, v2
	v_mov_b32_e32 v66, v2
	v_mov_b32_e32 v67, v2
	v_mov_b32_e32 v68, v2
	v_mov_b32_e32 v69, v2
	v_mov_b32_e32 v70, v2
	v_mov_b32_e32 v71, v2
	v_mov_b32_e32 v72, v2
	v_mov_b32_e32 v73, v2
	v_mov_b32_e32 v74, v2
	v_mov_b32_e32 v75, v2
	v_mov_b32_e32 v76, v2
	v_mov_b32_e32 v77, v2
	v_mov_b32_e32 v82, v2
	v_mov_b32_e32 v83, v2
	v_mov_b32_e32 v84, v2
	v_mov_b32_e32 v85, v2
	v_mov_b32_e32 v90, v2
	v_mov_b32_e32 v91, v2
	v_mov_b32_e32 v92, v2
	v_mov_b32_e32 v93, v2
	v_mov_b32_e32 v98, v2
	v_mov_b32_e32 v99, v2
	v_mov_b32_e32 v100, v2
	v_mov_b32_e32 v101, v2
	v_mov_b32_e32 v106, v2
	v_mov_b32_e32 v107, v2
	v_mov_b32_e32 v108, v2
	v_mov_b32_e32 v109, v2
	v_mov_b32_e32 v114, v2
	v_mov_b32_e32 v115, v2
	v_mov_b32_e32 v116, v2
	v_mov_b32_e32 v117, v2
	v_mov_b32_e32 v78, v2
	v_mov_b32_e32 v79, v2
	v_mov_b32_e32 v80, v2
	v_mov_b32_e32 v81, v2
	v_mov_b32_e32 v86, v2
	v_mov_b32_e32 v87, v2
	v_mov_b32_e32 v88, v2
	v_mov_b32_e32 v89, v2
	v_mov_b32_e32 v94, v2
	v_mov_b32_e32 v95, v2
	v_mov_b32_e32 v96, v2
	v_mov_b32_e32 v97, v2
	v_mov_b32_e32 v102, v2
	v_mov_b32_e32 v103, v2
	v_mov_b32_e32 v104, v2
	v_mov_b32_e32 v105, v2
	v_mov_b32_e32 v110, v2
	v_mov_b32_e32 v111, v2
	v_mov_b32_e32 v112, v2
	v_mov_b32_e32 v113, v2
	v_mov_b32_e32 v118, v2
	v_mov_b32_e32 v119, v2
	v_mov_b32_e32 v120, v2
	v_mov_b32_e32 v121, v2
	v_mov_b32_e32 v122, v2
	v_mov_b32_e32 v123, v2
	v_mov_b32_e32 v124, v2
	v_mov_b32_e32 v125, v2
	v_mov_b32_e32 v126, v2
	v_mov_b32_e32 v127, v2
	v_mov_b32_e32 v128, v2
	v_mov_b32_e32 v129, v2
	.p2align	6

; #define LAS __attribute__((address_space(3)))
; __device__ __forceinline__ void ssd_item(const Args& a, LAS unsigned char* lds, int layer, bool is_sample, int b, int h, int seq_row0, int nchunks,
;                                          bf16_t* proj, float* ssq, const int tid) {
;     ...
;     for (int c = 0; c < nchunks; ++c) {
;         const unsigned cs = (unsigned)c * SSD_STEP;
;         const LAS float* dtv = dt_all + c * 64; const LAS float* acv = ac_all + c * 64;
;     ...
;         const u32x4 bo0 = bv0, bo1 = bv1;
;         if (c + 1 < nchunks) {
;             const unsigned cn = cs + SSD_STEP;
;             xv = *(const u32x4*)(pbase + off_x + cn); if (tid < 24) xh = *(const u32x4*)(pbase + off_x + cn - 3u * PN * 2u);
;             bv0 = *(const u32x4*)(pbase + off_b + cn); bv1 = *(const u32x4*)(pbase + off_b + cn + PN * 2); cv0 = *(const u32x4*)(pbase + off_b + cn + 1024); cv1 = *(const u32x4*)(pbase + off_b + cn + PN * 2 + 1024);
;             zv = *(const u32x4*)(pbase + off_z + cn);
.LBB0_560:
	s_or_b64 exec, exec, s[20:21]
	s_addk_i32 s15, 0x100
	s_add_u32 s16, s16, 0x118000
	s_addc_u32 s17, s17, 0
	s_add_i32 s64, s64, 1
	s_waitcnt vmcnt(4)
	v_mov_b64_e32 v[58:59], v[86:87]
	s_waitcnt vmcnt(2)
	v_mov_b64_e32 v[62:63], v[90:91]
	s_cmpk_eq_i32 s15, 0x2000
	v_mov_b64_e32 v[60:61], v[88:89]
	v_mov_b64_e32 v[64:65], v[92:93]
	s_cbranch_scc1 .LBB0_580
	.p2align	6

; template <class Epi, bool GS = false>
; __device__ __forceinline__ void gemm_phase(LAS unsigned char* lds, const Gemm g, const StaticOrder& S, const Epi& E, const int tid) {
;     ...
;         for (int tg = 0; tg < nt; tg += seg) {
;         for (int t = tg; t < tg + seg; t += 2) {
.LBB0_665:
	s_mov_b32 s68, s61
	s_add_i32 s61, s61, s63
	s_mov_b32 s69, s67
	s_mov_b64 s[4:5], s[20:21]
	.p2align	6

;     __device__ __forceinline__ const char* Ap(int part) const { return (const char*)A0 + (long)(part == 1) * ((const char*)A1 - (const char*)A0) + (long)(part == 2) * ((const char*)A2 - (const char*)A0); }
;     __device__ __forceinline__ const char* Bp(int part) const { return (const char*)B0 + (long)(part == 1) * ((const char*)B1 - (const char*)B0) + (long)(part == 2) * ((const char*)B2 - (const char*)B0); }
; template <class Epi, bool GS = false>
; __device__ __forceinline__ void gemm_phase(LAS unsigned char* lds, const Gemm g, const StaticOrder& S, const Epi& E, const int tid) {
;     ...
;         const bool has_next = S.next(ui + 1, nxt);
;         const char* nA = has_next ? g.Ap(nxt.part) + (size_t)nxt.pm * tstepA : cA; const char* nB = has_next ? g.Bp(nxt.part) + (size_t)nxt.pn * tstepB : cB;
;         const int nt = g.Kp(cur.part) / BK;
;         const int seg = (GS && cur.part == 0) ? 8 : nt;
;         for (int tg = 0; tg < nt; tg += seg) {
;         for (int t = tg; t < tg + seg; t += 2) {
;             const bool last = (t == nt - 2);
;             const char* a1 = cA + (size_t)(t + 1) * kstep;
;             const char* a2 = last ? nA : cA + (size_t)(t + 2) * kstep; const char* b2 = last ? nB : cB + (size_t)(t + 2) * kstep;
;             const char* a3 = a2 + kstep; const char* b3 = b2 + kstep;
;     ...
; #pragma unroll
;         for (int a = 0; a < 2; ++a)
; #pragma unroll
;             for (int b = 0; b < 2; ++b)
; #pragma unroll
;                 for (int m = 0; m < 4; ++m)
; #pragma unroll
;                     for (int n = 0; n < 2; ++n) acc[a][b][m][n] = (f32x4){0.f, 0.f, 0.f, 0.f};
.Lks6_b:
	s_and_b64 s[46:47], s[4:5], exec
	s_cselect_b32 s15, s23, s45
	s_cselect_b32 s54, s22, s44
	s_add_u32 s42, s42, 0x40080
	s_addc_u32 s43, s43, 0
	s_add_u32 s55, s44, 0x100
	v_mov_b32_e32 v2, 0
	s_addc_u32 s56, s45, 0
	s_mov_b32 s57, -2
	s_cmp_eq_u32 s100, 0
	s_cselect_b32 s57, s57, 6
	v_mov_b32_e32 v3, v2
	v_mov_b32_e32 v4, v2
	v_mov_b32_e32 v5, v2
	v_mov_b32_e32 v6, v2
	v_mov_b32_e32 v7, v2
	v_mov_b32_e32 v8, v2
	v_mov_b32_e32 v9, v2
	v_mov_b32_e32 v18, v2
	v_mov_b32_e32 v19, v2
	v_mov_b32_e32 v20, v2
	v_mov_b32_e32 v21, v2
	v_mov_b32_e32 v22, v2
	v_mov_b32_e32 v23, v2
	v_mov_b32_e32 v24, v2
	v_mov_b32_e32 v25, v2
	v_mov_b32_e32 v34, v2
	v_mov_b32_e32 v35, v2
	v_mov_b32_e32 v36, v2
	v_mov_b32_e32 v37, v2
	v_mov_b32_e32 v38, v2
	v_mov_b32_e32 v39, v2
	v_mov_b32_e32 v40, v2
	v_mov_b32_e32 v41, v2
	s_waitcnt vmcnt(0)
	v_mov_b32_e32 v50, v2
	v_mov_b32_e32 v51, v2
	v_mov_b32_e32 v52, v2
	v_mov_b32_e32 v53, v2
	v_mov_b32_e32 v54, v2
	v_mov_b32_e32 v55, v2
	v_mov_b32_e32 v56, v2
	v_mov_b32_e32 v57, v2
	v_mov_b32_e32 v10, v2
	v_mov_b32_e32 v11, v2
	v_mov_b32_e32 v12, v2
	v_mov_b32_e32 v13, v2
	v_mov_b32_e32 v14, v2
	v_mov_b32_e32 v15, v2
	v_mov_b32_e32 v16, v2
	v_mov_b32_e32 v17, v2
	v_mov_b32_e32 v26, v2
	v_mov_b32_e32 v27, v2
	v_mov_b32_e32 v28, v2
	v_mov_b32_e32 v29, v2
	v_mov_b32_e32 v30, v2
	v_mov_b32_e32 v31, v2
	v_mov_b32_e32 v32, v2
	v_mov_b32_e32 v33, v2
	v_mov_b32_e32 v42, v2
	v_mov_b32_e32 v43, v2
	v_mov_b32_e32 v44, v2
	v_mov_b32_e32 v45, v2
	v_mov_b32_e32 v46, v2
	v_mov_b32_e32 v47, v2
	v_mov_b32_e32 v48, v2
	v_mov_b32_e32 v49, v2
	v_mov_b32_e32 v58, v2
	v_mov_b32_e32 v59, v2
	v_mov_b32_e32 v60, v2
	v_mov_b32_e32 v61, v2
	v_mov_b32_e32 v62, v2
	v_mov_b32_e32 v63, v2
	v_mov_b32_e32 v64, v2
	v_mov_b32_e32 v65, v2
	v_mov_b32_e32 v66, v2
	v_mov_b32_e32 v67, v2
	v_mov_b32_e32 v68, v2
	v_mov_b32_e32 v69, v2
	v_mov_b32_e32 v70, v2
	v_mov_b32_e32 v71, v2
	v_mov_b32_e32 v72, v2
	v_mov_b32_e32 v73, v2
	v_mov_b32_e32 v74, v2
	v_mov_b32_e32 v75, v2
	v_mov_b32_e32 v76, v2
	v_mov_b32_e32 v77, v2
	v_mov_b32_e32 v86, v2
	v_mov_b32_e32 v87, v2
	v_mov_b32_e32 v88, v2
	v_mov_b32_e32 v89, v2
	v_mov_b32_e32 v98, v2
	v_mov_b32_e32 v99, v2
	v_mov_b32_e32 v100, v2
	v_mov_b32_e32 v101, v2
	v_mov_b32_e32 v102, v2
	v_mov_b32_e32 v103, v2
	v_mov_b32_e32 v104, v2
	v_mov_b32_e32 v105, v2
	v_mov_b32_e32 v114, v2
	v_mov_b32_e32 v115, v2
	v_mov_b32_e32 v116, v2
	v_mov_b32_e32 v117, v2
	v_mov_b32_e32 v118, v2
	v_mov_b32_e32 v119, v2
	v_mov_b32_e32 v120, v2
	v_mov_b32_e32 v121, v2
	v_mov_b32_e32 v78, v2
	v_mov_b32_e32 v79, v2
	v_mov_b32_e32 v80, v2
	v_mov_b32_e32 v81, v2
	v_mov_b32_e32 v82, v2
	v_mov_b32_e32 v83, v2
	v_mov_b32_e32 v84, v2
	v_mov_b32_e32 v85, v2
	v_mov_b32_e32 v90, v2
	v_mov_b32_e32 v91, v2
	v_mov_b32_e32 v92, v2
	v_mov_b32_e32 v93, v2
	v_mov_b32_e32 v94, v2
	v_mov_b32_e32 v95, v2
	v_mov_b32_e32 v96, v2
	v_mov_b32_e32 v97, v2
	v_mov_b32_e32 v106, v2
	v_mov_b32_e32 v107, v2
	v_mov_b32_e32 v108, v2
	v_mov_b32_e32 v109, v2
	v_mov_b32_e32 v110, v2
	v_mov_b32_e32 v111, v2
	v_mov_b32_e32 v112, v2
	v_mov_b32_e32 v113, v2
	v_mov_b32_e32 v122, v2
	v_mov_b32_e32 v123, v2
	v_mov_b32_e32 v124, v2
	v_mov_b32_e32 v125, v2
	v_mov_b32_e32 v126, v2
	v_mov_b32_e32 v127, v2
	v_mov_b32_e32 v128, v2
	v_mov_b32_e32 v129, v2
	.p2align	6

;     __device__ __forceinline__ const char* Ap(int part) const { return (const char*)A0 + (long)(part == 1) * ((const char*)A1 - (const char*)A0) + (long)(part == 2) * ((const char*)A2 - (const char*)A0); }
;     __device__ __forceinline__ const char* Bp(int part) const { return (const char*)B0 + (long)(part == 1) * ((const char*)B1 - (const char*)B0) + (long)(part == 2) * ((const char*)B2 - (const char*)B0); }
; template <class Epi, bool GS = false>
; __device__ __forceinline__ void gemm_phase(LAS unsigned char* lds, const Gemm g, const StaticOrder& S, const Epi& E, const int tid) {
;     ...
;         const bool has_next = S.next(ui + 1, nxt);
;         const char* nA = has_next ? g.Ap(nxt.part) + (size_t)nxt.pm * tstepA : cA; const char* nB = has_next ? g.Bp(nxt.part) + (size_t)nxt.pn * tstepB : cB;
;         const int nt = g.Kp(cur.part) / BK;
;         const int seg = (GS && cur.part == 0) ? 8 : nt;
;         for (int tg = 0; tg < nt; tg += seg) {
;         for (int t = tg; t < tg + seg; t += 2) {
;             const bool last = (t == nt - 2);
;             const char* a1 = cA + (size_t)(t + 1) * kstep;
;             const char* a2 = last ? nA : cA + (size_t)(t + 2) * kstep; const char* b2 = last ? nB : cB + (size_t)(t + 2) * kstep;
;             const char* a3 = a2 + kstep; const char* b3 = b2 + kstep;
;     ...
; #pragma unroll
;         for (int a = 0; a < 2; ++a)
; #pragma unroll
;             for (int b = 0; b < 2; ++b)
; #pragma unroll
;                 for (int m = 0; m < 4; ++m)
; #pragma unroll
;                     for (int n = 0; n < 2; ++n) acc[a][b][m][n] = (f32x4){0.f, 0.f, 0.f, 0.f};
.LBB0_920:
	s_add_i32 s16, s14, 0x48
	s_add_i32 s17, s14, 0xffffffc0
	s_cmp_lt_i32 s14, 64
	s_cselect_b32 s16, s16, s17
	s_ashr_i32 s17, s16, 31
	s_lshl_b64 s[16:17], s[16:17], 19
	s_add_u32 s16, s12, s16
	s_addc_u32 s17, s13, s17
	s_and_b64 s[20:21], s[38:39], exec
	s_cselect_b32 s15, s17, s23
	s_cselect_b32 s47, s16, s22
	s_ashr_i32 s9, s8, 31
	s_lshl_b64 s[20:21], s[8:9], 19
	s_add_u32 s20, s2, s20
	s_addc_u32 s21, s3, s21
	s_and_b64 s[34:35], s[38:39], exec
	s_cselect_b32 s9, s21, s31
	s_cselect_b32 s48, s20, s30
	s_add_u32 s22, s22, 0x40080
	s_addc_u32 s23, s23, 0
	s_add_u32 s49, s30, 0x100
	v_mov_b32_e32 v2, 0
	s_addc_u32 s50, s31, 0
	s_mov_b32 s51, -2
	v_mov_b32_e32 v3, v2
	v_mov_b32_e32 v4, v2
	v_mov_b32_e32 v5, v2
	v_mov_b32_e32 v10, v2
	v_mov_b32_e32 v11, v2
	v_mov_b32_e32 v12, v2
	v_mov_b32_e32 v13, v2
	v_mov_b32_e32 v18, v2
	v_mov_b32_e32 v19, v2
	v_mov_b32_e32 v20, v2
	v_mov_b32_e32 v21, v2
	v_mov_b32_e32 v26, v2
	v_mov_b32_e32 v27, v2
	v_mov_b32_e32 v28, v2
	v_mov_b32_e32 v29, v2
	v_mov_b32_e32 v34, v2
	v_mov_b32_e32 v35, v2
	v_mov_b32_e32 v36, v2
	v_mov_b32_e32 v37, v2
	v_mov_b32_e32 v42, v2
	v_mov_b32_e32 v43, v2
	v_mov_b32_e32 v44, v2
	v_mov_b32_e32 v45, v2
	v_mov_b32_e32 v50, v2
	v_mov_b32_e32 v51, v2
	v_mov_b32_e32 v52, v2
	v_mov_b32_e32 v53, v2
	v_mov_b32_e32 v58, v2
	v_mov_b32_e32 v59, v2
	v_mov_b32_e32 v60, v2
	v_mov_b32_e32 v61, v2
	v_mov_b32_e32 v6, v2
	v_mov_b32_e32 v7, v2
	v_mov_b32_e32 v8, v2
	v_mov_b32_e32 v9, v2
	v_mov_b32_e32 v14, v2
	v_mov_b32_e32 v15, v2
	v_mov_b32_e32 v16, v2
	v_mov_b32_e32 v17, v2
	v_mov_b32_e32 v22, v2
	v_mov_b32_e32 v23, v2
	v_mov_b32_e32 v24, v2
	v_mov_b32_e32 v25, v2
	v_mov_b32_e32 v30, v2
	v_mov_b32_e32 v31, v2
	v_mov_b32_e32 v32, v2
	v_mov_b32_e32 v33, v2
	v_mov_b32_e32 v38, v2
	v_mov_b32_e32 v39, v2
	v_mov_b32_e32 v40, v2
	v_mov_b32_e32 v41, v2
	v_mov_b32_e32 v46, v2
	v_mov_b32_e32 v47, v2
	v_mov_b32_e32 v48, v2
	v_mov_b32_e32 v49, v2
	v_mov_b32_e32 v54, v2
	v_mov_b32_e32 v55, v2
	v_mov_b32_e32 v56, v2
	v_mov_b32_e32 v57, v2
	v_mov_b32_e32 v62, v2
	v_mov_b32_e32 v63, v2
	v_mov_b32_e32 v64, v2
	v_mov_b32_e32 v65, v2
	v_mov_b32_e32 v66, v2
	v_mov_b32_e32 v67, v2
	v_mov_b32_e32 v68, v2
	v_mov_b32_e32 v69, v2
	v_mov_b32_e32 v74, v2
	v_mov_b32_e32 v75, v2
	v_mov_b32_e32 v76, v2
	v_mov_b32_e32 v77, v2
	v_mov_b32_e32 v82, v2
	v_mov_b32_e32 v83, v2
	v_mov_b32_e32 v84, v2
	v_mov_b32_e32 v85, v2
	v_mov_b32_e32 v90, v2
	v_mov_b32_e32 v91, v2
	v_mov_b32_e32 v92, v2
	v_mov_b32_e32 v93, v2
	v_mov_b32_e32 v98, v2
	v_mov_b32_e32 v99, v2
	v_mov_b32_e32 v100, v2
	v_mov_b32_e32 v101, v2
	v_mov_b32_e32 v106, v2
	v_mov_b32_e32 v107, v2
	v_mov_b32_e32 v108, v2
	v_mov_b32_e32 v109, v2
	v_mov_b32_e32 v114, v2
	v_mov_b32_e32 v115, v2
	v_mov_b32_e32 v116, v2
	v_mov_b32_e32 v117, v2
	v_mov_b32_e32 v122, v2
	v_mov_b32_e32 v123, v2
	v_mov_b32_e32 v124, v2
	v_mov_b32_e32 v125, v2
	v_mov_b32_e32 v70, v2
	v_mov_b32_e32 v71, v2
	v_mov_b32_e32 v72, v2
	v_mov_b32_e32 v73, v2
	v_mov_b32_e32 v78, v2
	v_mov_b32_e32 v79, v2
	v_mov_b32_e32 v80, v2
	v_mov_b32_e32 v81, v2
	v_mov_b32_e32 v86, v2
	v_mov_b32_e32 v87, v2
	v_mov_b32_e32 v88, v2
	v_mov_b32_e32 v89, v2
	v_mov_b32_e32 v94, v2
	v_mov_b32_e32 v95, v2
	v_mov_b32_e32 v96, v2
	v_mov_b32_e32 v97, v2
	v_mov_b32_e32 v102, v2
	v_mov_b32_e32 v103, v2
	v_mov_b32_e32 v104, v2
	v_mov_b32_e32 v105, v2
	v_mov_b32_e32 v110, v2
	v_mov_b32_e32 v111, v2
	v_mov_b32_e32 v112, v2
	v_mov_b32_e32 v113, v2
	v_mov_b32_e32 v118, v2
	v_mov_b32_e32 v119, v2
	v_mov_b32_e32 v120, v2
	v_mov_b32_e32 v121, v2
	v_mov_b32_e32 v126, v2
	v_mov_b32_e32 v127, v2
	v_mov_b32_e32 v128, v2
	v_mov_b32_e32 v129, v2
	.p2align	6

;     __device__ __forceinline__ const char* Ap(int part) const { return (const char*)A0 + (long)(part == 1) * ((const char*)A1 - (const char*)A0) + (long)(part == 2) * ((const char*)A2 - (const char*)A0); }
;     __device__ __forceinline__ const char* Bp(int part) const { return (const char*)B0 + (long)(part == 1) * ((const char*)B1 - (const char*)B0) + (long)(part == 2) * ((const char*)B2 - (const char*)B0); }
; template <class Epi, bool GS = false>
; __device__ __forceinline__ void gemm_phase(LAS unsigned char* lds, const Gemm g, const StaticOrder& S, const Epi& E, const int tid) {
;     ...
;         const bool has_next = S.next(ui + 1, nxt);
;         const char* nA = has_next ? g.Ap(nxt.part) + (size_t)nxt.pm * tstepA : cA; const char* nB = has_next ? g.Bp(nxt.part) + (size_t)nxt.pn * tstepB : cB;
;         const int nt = g.Kp(cur.part) / BK;
;         const int seg = (GS && cur.part == 0) ? 8 : nt;
;         for (int tg = 0; tg < nt; tg += seg) {
;         for (int t = tg; t < tg + seg; t += 2) {
;             const bool last = (t == nt - 2);
;             const char* a1 = cA + (size_t)(t + 1) * kstep;
;             const char* a2 = last ? nA : cA + (size_t)(t + 2) * kstep; const char* b2 = last ? nB : cB + (size_t)(t + 2) * kstep;
;             const char* a3 = a2 + kstep; const char* b3 = b2 + kstep;
;     ...
; #pragma unroll
;         for (int a = 0; a < 2; ++a)
; #pragma unroll
;             for (int b = 0; b < 2; ++b)
; #pragma unroll
;                 for (int m = 0; m < 4; ++m)
; #pragma unroll
;                     for (int n = 0; n < 2; ++n) acc[a][b][m][n] = (f32x4){0.f, 0.f, 0.f, 0.f};
.Lks9_b:
.LBB0_992:
	s_add_u32 s50, s22, 0x100
	v_mov_b32_e32 v2, 0
	s_addc_u32 s51, s23, 0
	s_mov_b32 s52, -2
	s_cmp_eq_u32 s100, 0
	s_cselect_b32 s52, s52, 20
	v_mov_b32_e32 v3, v2
	v_mov_b32_e32 v4, v2
	v_mov_b32_e32 v5, v2
	v_mov_b32_e32 v6, v2
	v_mov_b32_e32 v7, v2
	v_mov_b32_e32 v8, v2
	v_mov_b32_e32 v9, v2
	v_mov_b32_e32 v18, v2
	v_mov_b32_e32 v19, v2
	v_mov_b32_e32 v20, v2
	v_mov_b32_e32 v21, v2
	v_mov_b32_e32 v22, v2
	v_mov_b32_e32 v23, v2
	v_mov_b32_e32 v24, v2
	v_mov_b32_e32 v25, v2
	v_mov_b32_e32 v34, v2
	v_mov_b32_e32 v35, v2
	v_mov_b32_e32 v36, v2
	v_mov_b32_e32 v37, v2
	v_mov_b32_e32 v38, v2
	v_mov_b32_e32 v39, v2
	v_mov_b32_e32 v40, v2
	v_mov_b32_e32 v41, v2
	v_mov_b32_e32 v50, v2
	v_mov_b32_e32 v51, v2
	v_mov_b32_e32 v52, v2
	v_mov_b32_e32 v53, v2
	v_mov_b32_e32 v54, v2
	v_mov_b32_e32 v55, v2
	v_mov_b32_e32 v56, v2
	v_mov_b32_e32 v57, v2
	v_mov_b32_e32 v10, v2
	v_mov_b32_e32 v11, v2
	v_mov_b32_e32 v12, v2
	v_mov_b32_e32 v13, v2
	v_mov_b32_e32 v14, v2
	v_mov_b32_e32 v15, v2
	v_mov_b32_e32 v16, v2
	v_mov_b32_e32 v17, v2
	v_mov_b32_e32 v26, v2
	v_mov_b32_e32 v27, v2
	v_mov_b32_e32 v28, v2
	v_mov_b32_e32 v29, v2
	v_mov_b32_e32 v30, v2
	v_mov_b32_e32 v31, v2
	v_mov_b32_e32 v32, v2
	v_mov_b32_e32 v33, v2
	v_mov_b32_e32 v42, v2
	v_mov_b32_e32 v43, v2
	v_mov_b32_e32 v44, v2
	v_mov_b32_e32 v45, v2
	v_mov_b32_e32 v46, v2
	v_mov_b32_e32 v47, v2
	v_mov_b32_e32 v48, v2
	v_mov_b32_e32 v49, v2
	v_mov_b32_e32 v58, v2
	v_mov_b32_e32 v59, v2
	v_mov_b32_e32 v60, v2
	v_mov_b32_e32 v61, v2
	v_mov_b32_e32 v62, v2
	v_mov_b32_e32 v63, v2
	v_mov_b32_e32 v64, v2
	v_mov_b32_e32 v65, v2
	v_mov_b32_e32 v66, v2
	v_mov_b32_e32 v67, v2
	v_mov_b32_e32 v68, v2
	v_mov_b32_e32 v69, v2
	v_mov_b32_e32 v70, v2
	v_mov_b32_e32 v71, v2
	v_mov_b32_e32 v72, v2
	v_mov_b32_e32 v73, v2
	v_mov_b32_e32 v82, v2
	v_mov_b32_e32 v83, v2
	v_mov_b32_e32 v84, v2
	v_mov_b32_e32 v85, v2
	v_mov_b32_e32 v86, v2
	v_mov_b32_e32 v87, v2
	v_mov_b32_e32 v88, v2
	v_mov_b32_e32 v89, v2
	v_mov_b32_e32 v98, v2
	v_mov_b32_e32 v99, v2
	v_mov_b32_e32 v100, v2
	v_mov_b32_e32 v101, v2
	v_mov_b32_e32 v102, v2
	v_mov_b32_e32 v103, v2
	v_mov_b32_e32 v104, v2
	v_mov_b32_e32 v105, v2
	v_mov_b32_e32 v114, v2
	v_mov_b32_e32 v115, v2
	v_mov_b32_e32 v116, v2
	v_mov_b32_e32 v117, v2
	v_mov_b32_e32 v118, v2
	v_mov_b32_e32 v119, v2
	v_mov_b32_e32 v120, v2
	v_mov_b32_e32 v121, v2
	v_mov_b32_e32 v74, v2
	v_mov_b32_e32 v75, v2
	v_mov_b32_e32 v76, v2
	v_mov_b32_e32 v77, v2
	v_mov_b32_e32 v78, v2
	v_mov_b32_e32 v79, v2
	v_mov_b32_e32 v80, v2
	v_mov_b32_e32 v81, v2
	v_mov_b32_e32 v90, v2
	v_mov_b32_e32 v91, v2
	v_mov_b32_e32 v92, v2
	v_mov_b32_e32 v93, v2
	v_mov_b32_e32 v94, v2
	v_mov_b32_e32 v95, v2
	v_mov_b32_e32 v96, v2
	v_mov_b32_e32 v97, v2
	v_mov_b32_e32 v106, v2
	v_mov_b32_e32 v107, v2
	v_mov_b32_e32 v108, v2
	v_mov_b32_e32 v109, v2
	v_mov_b32_e32 v110, v2
	v_mov_b32_e32 v111, v2
	v_mov_b32_e32 v112, v2
	v_mov_b32_e32 v113, v2
	v_mov_b32_e32 v122, v2
	v_mov_b32_e32 v123, v2
	v_mov_b32_e32 v124, v2
	v_mov_b32_e32 v125, v2
	v_mov_b32_e32 v126, v2
	v_mov_b32_e32 v127, v2
	v_mov_b32_e32 v128, v2
	v_mov_b32_e32 v129, v2
	.p2align	6
